# v18 + P2 idle half-round converts w_o (moved out of P0), P17 idle round converts all of w_ffn_out (deepened loops)
# speedup vs baseline: 1.0024x; 1.0022x over previous
; __device__ __forceinline__ int win_src(int nb) { const int n0 = nb * 32; if (n0 < 1536) return n0; if (n0 < 1792) return n0 == 1536 ? 1536 : (n0 == 1664 ? 1568 : -1); return n0 - 192; }
; __global__ void __launch_bounds__(NWAVES * 64, 2) mk_fwd(Args args) {
;     ...
;         for (int it = gw; it < NITEMS; it += NGW) {
;             int r = it;
;             if (r < I_IN) { const int nblk = INP / 32, kb = r / nblk, nb = r % nblk; p0_item(in_w_in, INW, D, Win_t, win_src(nb), nb * 32, kb * 64, nullptr, scr, lane); continue; } r -= I_IN;
;             if (r < I_UQ) { const int nblk = 3072 / 32, kb = r / nblk, nb = r % nblk; p0_item(in_w_uq, 3072, 1024, Wuq_t, wuq_src(nb), nb * 32, kb * 64, in_q_norm_g, scr, lane); continue; } r -= I_UQ;
;             if (r < I_UKV) { const int nblk = 4096 / 32, kb = r / nblk, nb = r % nblk; p0_item(in_w_ukv, 4096, 512, Wukv_t, nb * 32, nb * 32, kb * 64, in_kv_norm_g, scr, lane); continue; } r -= I_UKV;
;             if (r < I_BM) { const int nblk = 4096 / 32, kb = r / nblk, nb = r % nblk; p0_item(in_w_br_mla, 4096, 2048, Wbm_t, nb * 32, nb * 32, kb * 64, nullptr, scr, lane); continue; } r -= I_BM;
;             if (r < 5 * I_SQ) { const int wsel = r / I_SQ; r -= wsel * I_SQ; const int nblk = 4096 / 32, kb = r / nblk, nb = r % nblk;
;                 const float* W = wsel == 0 ? in_w_br_ret : wsel == 1 ? in_w_o : wsel == 2 ? in_w_cq : wsel == 3 ? in_w_ck : in_w_cv;
;                 bf16_t* WT = wsel == 0 ? Wbr_t : wsel == 1 ? Wo_t : wsel == 2 ? Wcq_r : wsel == 3 ? Wck_t : Wcv_t;
;                 if (wsel == 2) p0_item_lnr(W, 4096, WT, nb * 32, kb * 64, in_ln1_g, in_ln1_b, S1V, C1V, lane);
;                 else p0_item(W, 4096, 4096, WT, nb * 32, nb * 32, kb * 64, nullptr, scr, lane);
.LBB0_13:
	s_add_i32 s25, s25, s72
	s_add_i32 s20, s20, s72
	s_add_i32 s18, s18, s21
	s_add_i32 s22, s22, s72
	s_add_i32 s64, s64, s72
	s_cmpk_lg_i32 s85, 0x100
	s_cbranch_scc1 .Lp0_noskip
	s_cmp_lt_i32 s25, 0xc800
	s_cbranch_scc1 .Lp0_noskip
	s_cmp_lt_i32 s25, 0x10800
	s_cbranch_scc1 .LBB0_13

; __device__ __forceinline__ int lane_id() { int l; asm volatile("v_mbcnt_lo_u32_b32 %0, -1, 0\n\tv_mbcnt_hi_u32_b32 %0, -1, %0" : "=v"(l)); return l; }
; #define CONV_WFO(lo_, hi_, w_, nw_) do { LAS float* scr_ = (LAS float*)(lds + wave * 16384); for (int r = (lo_) + (w_); r < (hi_); r += (nw_)) { const int nblk = 4096 / 32, kb = r / nblk, nb = r % nblk; \
;         p0_item(in_w_ffn_out, 4096, DFF, Wfo_t, nb * 32, nb * 32, kb * 64, nullptr, scr_, lane); } } while (0)
; __global__ void __launch_bounds__(NWAVES * 64, 2) mk_fwd(Args args) {
;     ...
;         { const int lane = lane_id(); if (split && bx >= 128) { CONV_WFO(0, I_FO_P2, (bx - 128) * NWAVES + wave, 128 * NWAVES); __syncthreads(); } }
.LBB0_355:
	v_readlane_b32 s6, v237, 53
	s_cmpk_lt_i32 s84, 0x80
	v_readlane_b32 s7, v237, 54
	s_cselect_b64 s[4:5], -1, 0
	s_xor_b64 s[6:7], s[6:7], -1
	s_or_b64 s[4:5], s[4:5], s[6:7]
	s_and_b64 vcc, exec, s[4:5]
	v_mbcnt_lo_u32_b32 v2, -1, 0
	v_mbcnt_hi_u32_b32 v2, -1, v2
	s_cbranch_vccnz .LBB0_366
	s_lshl_b32 s4, s84, 3
	s_add_i32 s4, s93, s4
	s_add_i32 s10, s4, 0xfffffc00
	s_cmpk_gt_i32 s10, 0x1fff
	s_cbranch_scc1 .LBB0_365
	v_and_b32_e32 v0, 7, v2
	v_lshlrev_b32_e32 v4, 4, v0
	s_waitcnt lgkmcnt(0)
	v_mov_b32_e32 v5, 0
	s_lshl_b32 s4, s93, 14
	v_ashrrev_i32_e32 v21, 3, v2
	v_mul_u32_u24_e32 v3, 0x420, v0
	v_lshl_add_u64 v[0:1], s[78:79], 0, v[4:5]
	s_mov_b64 s[6:7], 0x1d100000
	s_add_i32 s8, s4, 0
	v_ashrrev_i32_e32 v20, 5, v2
	v_lshl_add_u64 v[0:1], v[0:1], 0, s[6:7]
	v_lshlrev_b32_e32 v4, 2, v21
	s_movk_i32 s6, 0x84
	v_add3_u32 v22, s8, v3, v4
	v_mul_lo_u32 v3, v20, s6
	v_lshlrev_b32_e32 v2, 2, v2
	v_readlane_b32 s24, v236, 6
	v_add_u32_e32 v3, s4, v3
	v_and_b32_e32 v4, 0x7c, v2
	v_readlane_b32 s26, v236, 8
	v_readlane_b32 s27, v236, 9
	s_mov_b32 s5, 0
	v_add3_u32 v23, v3, v4, 0
	v_readlane_b32 s8, v237, 29
	v_readlane_b32 s9, v237, 30
	s_nop 1
	v_lshl_add_u64 v[2:3], s[8:9], 0, v[4:5]
	v_add_u32_e32 v24, 14, v20
	v_add_u32_e32 v25, 12, v20
	v_add_u32_e32 v26, 10, v20
	v_add_u32_e32 v27, 8, v20
	v_add_u32_e32 v28, 6, v20
	v_add_u32_e32 v29, 4, v20
	v_add_u32_e32 v30, 2, v20
	s_movk_i32 s11, 0x2000
	v_readlane_b32 s25, v236, 7
	v_readlane_b32 s28, v236, 10
	v_readlane_b32 s29, v236, 11
	v_readlane_b32 s30, v236, 12
	v_readlane_b32 s31, v236, 13
	s_branch .LBB0_359
.LBB0_358:
	s_add_i32 s4, s10, 0x400
	s_cmpk_gt_i32 s10, 0x1bff
	s_mov_b32 s10, s4
	s_cbranch_scc1 .LBB0_365

; #define LAS __attribute__((address_space(3)))
; #define LDS_WAIT() asm volatile("s_waitcnt lgkmcnt(0)" ::: "memory")
; __device__ __forceinline__ unsigned cvt_pk_bf16(float lo, float hi) { const f32x2 v = {lo, hi}; const bf16x2_t b = __builtin_convertvector(v, bf16x2_t); return __builtin_bit_cast(unsigned, b); }
; __device__ __forceinline__ void p0_item(const float* __restrict__ W, int ldw, int K, bf16_t* __restrict__ WT, int sc, int dn, int k0, const float* __restrict__ gk, LAS float* scr, int lane) {
;     const int c = lane & 7;
;     if (sc < 0) {
; #pragma unroll
;         for (int j = 0; j < 4; ++j) { const int n = (lane >> 3) + 8 * j; *(u32x4*)(WT + (size_t)(dn + n) * K + k0 + 8 * c) = (u32x4){0u, 0u, 0u, 0u}; }
;         return;
;     }
; #pragma unroll 8
;     for (int i = 0; i < 32; ++i) { const int kk = 2 * i + (lane >> 5); float v = __builtin_nontemporal_load(W + (size_t)(k0 + kk) * ldw + sc + (lane & 31)); if (gk) v *= gk[k0 + kk]; scr[kk * 33 + (lane & 31)] = v; }
;     LDS_WAIT(); asm volatile("" ::: "memory");
; #pragma unroll
;     for (int j = 0; j < 4; ++j) { const int n = (lane >> 3) + 8 * j; const LAS float* s = scr + (8 * c) * 33 + n;
;         u32x4 o; o.x = cvt_pk_bf16(s[0 * 33], s[1 * 33]); o.y = cvt_pk_bf16(s[2 * 33], s[3 * 33]); o.z = cvt_pk_bf16(s[4 * 33], s[5 * 33]); o.w = cvt_pk_bf16(s[6 * 33], s[7 * 33]);
;         __builtin_nontemporal_store(o, (u32x4*)(WT + (size_t)(dn + n) * K + k0 + 8 * c)); }
;     LDS_WAIT(); asm volatile("" ::: "memory");
; }
.LBB0_361:
	v_lshl_add_u64 v[32:33], v[18:19], 0, s[8:9]
	v_lshl_add_u64 v[34:35], v[16:17], 0, s[8:9]
	v_lshl_add_u64 v[36:37], v[14:15], 0, s[8:9]
	v_lshl_add_u64 v[38:39], v[12:13], 0, s[8:9]
	v_lshl_add_u64 v[40:41], v[10:11], 0, s[8:9]
	v_lshl_add_u64 v[42:43], v[8:9], 0, s[8:9]
	v_lshl_add_u64 v[44:45], v[6:7], 0, s[8:9]
	v_lshl_add_u64 v[46:47], v[4:5], 0, s[8:9]
	global_load_dword v176, v[32:33], off nt
	global_load_dword v177, v[34:35], off nt
	global_load_dword v178, v[36:37], off nt
	global_load_dword v179, v[38:39], off nt
	global_load_dword v180, v[40:41], off nt
	global_load_dword v181, v[42:43], off nt
	global_load_dword v182, v[44:45], off nt
	global_load_dword v183, v[46:47], off nt
	s_add_u32 s8, s8, 0x40000
	s_addc_u32 s9, s9, 0
	v_lshl_add_u64 v[32:33], v[18:19], 0, s[8:9]
	v_lshl_add_u64 v[34:35], v[16:17], 0, s[8:9]
	v_lshl_add_u64 v[36:37], v[14:15], 0, s[8:9]
	v_lshl_add_u64 v[38:39], v[12:13], 0, s[8:9]
	v_lshl_add_u64 v[40:41], v[10:11], 0, s[8:9]
	v_lshl_add_u64 v[42:43], v[8:9], 0, s[8:9]
	v_lshl_add_u64 v[44:45], v[6:7], 0, s[8:9]
	v_lshl_add_u64 v[46:47], v[4:5], 0, s[8:9]
	global_load_dword v184, v[32:33], off nt
	global_load_dword v185, v[34:35], off nt
	global_load_dword v186, v[36:37], off nt
	global_load_dword v187, v[38:39], off nt
	global_load_dword v188, v[40:41], off nt
	global_load_dword v189, v[42:43], off nt
	global_load_dword v190, v[44:45], off nt
	global_load_dword v191, v[46:47], off nt
	s_add_u32 s8, s8, 0x40000
	s_addc_u32 s9, s9, 0
	v_lshl_add_u64 v[32:33], v[18:19], 0, s[8:9]
	v_lshl_add_u64 v[34:35], v[16:17], 0, s[8:9]
	v_lshl_add_u64 v[36:37], v[14:15], 0, s[8:9]
	v_lshl_add_u64 v[38:39], v[12:13], 0, s[8:9]
	v_lshl_add_u64 v[40:41], v[10:11], 0, s[8:9]
	v_lshl_add_u64 v[42:43], v[8:9], 0, s[8:9]
	v_lshl_add_u64 v[44:45], v[6:7], 0, s[8:9]
	v_lshl_add_u64 v[46:47], v[4:5], 0, s[8:9]
	global_load_dword v192, v[32:33], off nt
	global_load_dword v193, v[34:35], off nt
	global_load_dword v194, v[36:37], off nt
	global_load_dword v195, v[38:39], off nt
	global_load_dword v196, v[40:41], off nt
	global_load_dword v197, v[42:43], off nt
	global_load_dword v198, v[44:45], off nt
	global_load_dword v199, v[46:47], off nt
	s_add_u32 s8, s8, 0x40000
	s_addc_u32 s9, s9, 0
	v_lshl_add_u64 v[32:33], v[18:19], 0, s[8:9]
	v_lshl_add_u64 v[34:35], v[16:17], 0, s[8:9]
	v_lshl_add_u64 v[36:37], v[14:15], 0, s[8:9]
	v_lshl_add_u64 v[38:39], v[12:13], 0, s[8:9]
	v_lshl_add_u64 v[40:41], v[10:11], 0, s[8:9]
	v_lshl_add_u64 v[42:43], v[8:9], 0, s[8:9]
	v_lshl_add_u64 v[44:45], v[6:7], 0, s[8:9]
	v_lshl_add_u64 v[46:47], v[4:5], 0, s[8:9]
	global_load_dword v200, v[32:33], off nt
	global_load_dword v201, v[34:35], off nt
	global_load_dword v202, v[36:37], off nt
	global_load_dword v203, v[38:39], off nt
	global_load_dword v204, v[40:41], off nt
	global_load_dword v205, v[42:43], off nt
	global_load_dword v206, v[44:45], off nt
	global_load_dword v207, v[46:47], off nt
	s_add_u32 s8, s8, 0x40000
	s_addc_u32 s9, s9, 0
	v_add_u32_e32 v40, 0x400, v31
	s_waitcnt vmcnt(30)
	ds_write2_b32 v31, v176, v177 offset1:66
	s_waitcnt vmcnt(28)
	ds_write2_b32 v31, v178, v179 offset0:132 offset1:198
	s_waitcnt vmcnt(26)
	ds_write2_b32 v40, v180, v181 offset0:8 offset1:74
	s_waitcnt vmcnt(24)
	ds_write2_b32 v40, v182, v183 offset0:140 offset1:206
	v_add_u32_e32 v31, 0x840, v31
	v_add_u32_e32 v40, 0x400, v31
	s_waitcnt vmcnt(22)
	ds_write2_b32 v31, v184, v185 offset1:66
	s_waitcnt vmcnt(20)
	ds_write2_b32 v31, v186, v187 offset0:132 offset1:198
	s_waitcnt vmcnt(18)
	ds_write2_b32 v40, v188, v189 offset0:8 offset1:74
	s_waitcnt vmcnt(16)
	ds_write2_b32 v40, v190, v191 offset0:140 offset1:206
	v_add_u32_e32 v31, 0x840, v31
	v_add_u32_e32 v40, 0x400, v31
	s_waitcnt vmcnt(14)
	ds_write2_b32 v31, v192, v193 offset1:66
	s_waitcnt vmcnt(12)
	ds_write2_b32 v31, v194, v195 offset0:132 offset1:198
	s_waitcnt vmcnt(10)
	ds_write2_b32 v40, v196, v197 offset0:8 offset1:74
	s_waitcnt vmcnt(8)
	ds_write2_b32 v40, v198, v199 offset0:140 offset1:206
	v_add_u32_e32 v31, 0x840, v31
	v_add_u32_e32 v40, 0x400, v31
	s_waitcnt vmcnt(6)
	ds_write2_b32 v31, v200, v201 offset1:66
	s_waitcnt vmcnt(4)
	ds_write2_b32 v31, v202, v203 offset0:132 offset1:198
	s_waitcnt vmcnt(2)
	ds_write2_b32 v40, v204, v205 offset0:8 offset1:74
	s_waitcnt vmcnt(0)
	ds_write2_b32 v40, v206, v207 offset0:140 offset1:206
	v_add_u32_e32 v31, 0x840, v31
	s_waitcnt lgkmcnt(0)
	ds_read2_b32 v[8:9], v22 offset0:33 offset1:41
	ds_read2_b32 v[10:11], v22 offset1:8
	ds_read2_b32 v[12:13], v22 offset0:66 offset1:74
	ds_read2_b32 v[14:15], v22 offset0:99 offset1:107
	ds_read2_b32 v[16:17], v22 offset0:132 offset1:140
	ds_read2_b32 v[18:19], v22 offset0:165 offset1:173
	ds_read2_b32 v[32:33], v22 offset0:198 offset1:206
	ds_read2_b32 v[34:35], v22 offset0:231 offset1:239
	s_ashr_i32 s7, s6, 31
	v_lshl_add_u64 v[36:37], s[6:7], 1, v[0:1]
	v_add_u32_e32 v31, s4, v21
	s_waitcnt lgkmcnt(6)
	v_cvt_pk_bf16_f32 v4, v10, v8
	s_waitcnt lgkmcnt(4)
	v_cvt_pk_bf16_f32 v5, v12, v14
	s_waitcnt lgkmcnt(2)
	v_cvt_pk_bf16_f32 v6, v16, v18
	s_waitcnt lgkmcnt(0)
	v_cvt_pk_bf16_f32 v7, v32, v34
	v_mad_i64_i32 v[38:39], s[8:9], v31, s11, v[36:37]
	global_store_dwordx4 v[38:39], v[4:7], off nt
	v_add_u32_e32 v8, 8, v31
	s_nop 0
	v_cvt_pk_bf16_f32 v4, v11, v9
	v_cvt_pk_bf16_f32 v5, v13, v15
	v_cvt_pk_bf16_f32 v6, v17, v19
	v_cvt_pk_bf16_f32 v7, v33, v35
	ds_read2_b32 v[10:11], v22 offset0:49 offset1:57
	ds_read2_b32 v[12:13], v22 offset0:16 offset1:24
	ds_read2_b32 v[14:15], v22 offset0:82 offset1:90
	ds_read2_b32 v[16:17], v22 offset0:115 offset1:123
	ds_read2_b32 v[18:19], v22 offset0:148 offset1:156
	ds_read2_b32 v[32:33], v22 offset0:181 offset1:189
	ds_read2_b32 v[34:35], v22 offset0:214 offset1:222
	ds_read2_b32 v[38:39], v22 offset0:247 offset1:255
	v_mad_i64_i32 v[8:9], s[8:9], v8, s11, v[36:37]
	global_store_dwordx4 v[8:9], v[4:7], off nt
	v_add_u32_e32 v8, 16, v31
	v_mad_i64_i32 v[8:9], s[8:9], v8, s11, v[36:37]
	s_waitcnt lgkmcnt(6)
	v_cvt_pk_bf16_f32 v4, v12, v10
	s_waitcnt lgkmcnt(4)
	v_cvt_pk_bf16_f32 v5, v14, v16
	s_waitcnt lgkmcnt(2)
	v_cvt_pk_bf16_f32 v6, v18, v32
	s_waitcnt lgkmcnt(0)
	v_cvt_pk_bf16_f32 v7, v34, v38
	global_store_dwordx4 v[8:9], v[4:7], off nt
	v_add_u32_e32 v8, 24, v31
	v_mad_i64_i32 v[8:9], s[8:9], v8, s11, v[36:37]
	v_cvt_pk_bf16_f32 v4, v13, v11
	v_cvt_pk_bf16_f32 v5, v15, v17
	v_cvt_pk_bf16_f32 v6, v19, v33
	v_cvt_pk_bf16_f32 v7, v35, v39
	global_store_dwordx4 v[8:9], v[4:7], off nt
	s_waitcnt lgkmcnt(0)
	s_branch .LBB0_358

; __device__ __forceinline__ int lane_id() { int l; asm volatile("v_mbcnt_lo_u32_b32 %0, -1, 0\n\tv_mbcnt_hi_u32_b32 %0, -1, %0" : "=v"(l)); return l; }
; #define CONV_WFO(lo_, hi_, w_, nw_) do { LAS float* scr_ = (LAS float*)(lds + wave * 16384); for (int r = (lo_) + (w_); r < (hi_); r += (nw_)) { const int nblk = 4096 / 32, kb = r / nblk, nb = r % nblk; \
;         p0_item(in_w_ffn_out, 4096, DFF, Wfo_t, nb * 32, nb * 32, kb * 64, nullptr, scr_, lane); } } while (0)
; __global__ void __launch_bounds__(NWAVES * 64, 2) mk_fwd(Args args) {
;     ...
;         const int lane = lane_id();
;         if (split && bx >= 192) CONV_WFO(I_FO_P2, I_FO, (bx - 192) * NWAVES + wave, 64 * NWAVES); }
.LBB0_1397:
	s_lshl_b32 s0, s84, 3
	s_add_i32 s4, s93, s0
	s_cmpk_gt_i32 s84, 0xbf
	v_readlane_b32 s2, v237, 53
	s_cselect_b64 s[0:1], -1, 0
	v_readlane_b32 s3, v237, 54
	s_and_b64 s[2:3], s[0:1], s[2:3]
	s_add_i32 s1, s4, 0xfffffa00
	s_cmpk_lt_i32 s1, 0x5600
	s_cselect_b64 s[4:5], -1, 0
	s_and_b64 s[2:3], s[2:3], s[4:5]
	s_movk_i32 s0, 0x5600
	s_andn2_b64 vcc, exec, s[2:3]
	s_waitcnt lgkmcnt(0)
	v_mbcnt_lo_u32_b32 v2, -1, 0
	v_mbcnt_hi_u32_b32 v2, -1, v2
	s_cbranch_vccnz .LBB0_1406
	v_and_b32_e32 v0, 7, v2
	v_lshlrev_b32_e32 v4, 4, v0
	v_mov_b32_e32 v5, 0
	s_lshl_b32 s4, s93, 14
	v_ashrrev_i32_e32 v21, 3, v2
	v_mul_u32_u24_e32 v3, 0x420, v0
	v_lshl_add_u64 v[0:1], s[78:79], 0, v[4:5]
	s_mov_b64 s[2:3], 0x15b00000
	s_add_i32 s6, s4, 0
	v_ashrrev_i32_e32 v20, 5, v2
	v_lshl_add_u64 v[0:1], v[0:1], 0, s[2:3]
	v_lshlrev_b32_e32 v4, 2, v21
	s_movk_i32 s2, 0x84
	v_add3_u32 v22, s6, v3, v4
	v_mul_lo_u32 v3, v20, s2
	v_lshlrev_b32_e32 v2, 2, v2
	v_add_u32_e32 v3, s4, v3
	v_and_b32_e32 v4, 0x7c, v2
	s_mov_b32 s5, 0
	v_add3_u32 v23, v3, v4, 0
	v_lshl_add_u64 v[2:3], s[46:47], 0, v[4:5]
	v_add_u32_e32 v24, 14, v20
	v_add_u32_e32 v25, 12, v20
	v_add_u32_e32 v26, 10, v20
	v_add_u32_e32 v27, 8, v20
	v_add_u32_e32 v28, 6, v20
	v_add_u32_e32 v29, 4, v20
	v_add_u32_e32 v30, 2, v20
	s_branch .LBB0_1400

; #define LAS __attribute__((address_space(3)))
; #define LDS_WAIT() asm volatile("s_waitcnt lgkmcnt(0)" ::: "memory")
; __device__ __forceinline__ unsigned cvt_pk_bf16(float lo, float hi) { const f32x2 v = {lo, hi}; const bf16x2_t b = __builtin_convertvector(v, bf16x2_t); return __builtin_bit_cast(unsigned, b); }
; __device__ __forceinline__ void p0_item(const float* __restrict__ W, int ldw, int K, bf16_t* __restrict__ WT, int sc, int dn, int k0, const float* __restrict__ gk, LAS float* scr, int lane) {
;     const int c = lane & 7;
;     if (sc < 0) {
; #pragma unroll
;         for (int j = 0; j < 4; ++j) { const int n = (lane >> 3) + 8 * j; *(u32x4*)(WT + (size_t)(dn + n) * K + k0 + 8 * c) = (u32x4){0u, 0u, 0u, 0u}; }
;         return;
;     }
; #pragma unroll 8
;     for (int i = 0; i < 32; ++i) { const int kk = 2 * i + (lane >> 5); float v = __builtin_nontemporal_load(W + (size_t)(k0 + kk) * ldw + sc + (lane & 31)); if (gk) v *= gk[k0 + kk]; scr[kk * 33 + (lane & 31)] = v; }
;     LDS_WAIT(); asm volatile("" ::: "memory");
; #pragma unroll
;     for (int j = 0; j < 4; ++j) { const int n = (lane >> 3) + 8 * j; const LAS float* s = scr + (8 * c) * 33 + n;
;         u32x4 o; o.x = cvt_pk_bf16(s[0 * 33], s[1 * 33]); o.y = cvt_pk_bf16(s[2 * 33], s[3 * 33]); o.z = cvt_pk_bf16(s[4 * 33], s[5 * 33]); o.w = cvt_pk_bf16(s[6 * 33], s[7 * 33]);
;         __builtin_nontemporal_store(o, (u32x4*)(WT + (size_t)(dn + n) * K + k0 + 8 * c)); }
;     LDS_WAIT(); asm volatile("" ::: "memory");
; }
.LBB0_1402:
	v_lshl_add_u64 v[32:33], v[18:19], 0, s[6:7]
	v_lshl_add_u64 v[34:35], v[16:17], 0, s[6:7]
	v_lshl_add_u64 v[36:37], v[14:15], 0, s[6:7]
	v_lshl_add_u64 v[38:39], v[12:13], 0, s[6:7]
	v_lshl_add_u64 v[40:41], v[10:11], 0, s[6:7]
	v_lshl_add_u64 v[42:43], v[8:9], 0, s[6:7]
	v_lshl_add_u64 v[44:45], v[6:7], 0, s[6:7]
	v_lshl_add_u64 v[46:47], v[4:5], 0, s[6:7]
	global_load_dword v176, v[32:33], off nt
	global_load_dword v177, v[34:35], off nt
	global_load_dword v178, v[36:37], off nt
	global_load_dword v179, v[38:39], off nt
	global_load_dword v180, v[40:41], off nt
	global_load_dword v181, v[42:43], off nt
	global_load_dword v182, v[44:45], off nt
	global_load_dword v183, v[46:47], off nt
	s_add_u32 s6, s6, 0x40000
	s_addc_u32 s7, s7, 0
	v_lshl_add_u64 v[32:33], v[18:19], 0, s[6:7]
	v_lshl_add_u64 v[34:35], v[16:17], 0, s[6:7]
	v_lshl_add_u64 v[36:37], v[14:15], 0, s[6:7]
	v_lshl_add_u64 v[38:39], v[12:13], 0, s[6:7]
	v_lshl_add_u64 v[40:41], v[10:11], 0, s[6:7]
	v_lshl_add_u64 v[42:43], v[8:9], 0, s[6:7]
	v_lshl_add_u64 v[44:45], v[6:7], 0, s[6:7]
	v_lshl_add_u64 v[46:47], v[4:5], 0, s[6:7]
	global_load_dword v184, v[32:33], off nt
	global_load_dword v185, v[34:35], off nt
	global_load_dword v186, v[36:37], off nt
	global_load_dword v187, v[38:39], off nt
	global_load_dword v188, v[40:41], off nt
	global_load_dword v189, v[42:43], off nt
	global_load_dword v190, v[44:45], off nt
	global_load_dword v191, v[46:47], off nt
	s_add_u32 s6, s6, 0x40000
	s_addc_u32 s7, s7, 0
	v_lshl_add_u64 v[32:33], v[18:19], 0, s[6:7]
	v_lshl_add_u64 v[34:35], v[16:17], 0, s[6:7]
	v_lshl_add_u64 v[36:37], v[14:15], 0, s[6:7]
	v_lshl_add_u64 v[38:39], v[12:13], 0, s[6:7]
	v_lshl_add_u64 v[40:41], v[10:11], 0, s[6:7]
	v_lshl_add_u64 v[42:43], v[8:9], 0, s[6:7]
	v_lshl_add_u64 v[44:45], v[6:7], 0, s[6:7]
	v_lshl_add_u64 v[46:47], v[4:5], 0, s[6:7]
	global_load_dword v192, v[32:33], off nt
	global_load_dword v193, v[34:35], off nt
	global_load_dword v194, v[36:37], off nt
	global_load_dword v195, v[38:39], off nt
	global_load_dword v196, v[40:41], off nt
	global_load_dword v197, v[42:43], off nt
	global_load_dword v198, v[44:45], off nt
	global_load_dword v199, v[46:47], off nt
	s_add_u32 s6, s6, 0x40000
	s_addc_u32 s7, s7, 0
	v_lshl_add_u64 v[32:33], v[18:19], 0, s[6:7]
	v_lshl_add_u64 v[34:35], v[16:17], 0, s[6:7]
	v_lshl_add_u64 v[36:37], v[14:15], 0, s[6:7]
	v_lshl_add_u64 v[38:39], v[12:13], 0, s[6:7]
	v_lshl_add_u64 v[40:41], v[10:11], 0, s[6:7]
	v_lshl_add_u64 v[42:43], v[8:9], 0, s[6:7]
	v_lshl_add_u64 v[44:45], v[6:7], 0, s[6:7]
	v_lshl_add_u64 v[46:47], v[4:5], 0, s[6:7]
	global_load_dword v200, v[32:33], off nt
	global_load_dword v201, v[34:35], off nt
	global_load_dword v202, v[36:37], off nt
	global_load_dword v203, v[38:39], off nt
	global_load_dword v204, v[40:41], off nt
	global_load_dword v205, v[42:43], off nt
	global_load_dword v206, v[44:45], off nt
	global_load_dword v207, v[46:47], off nt
	s_add_u32 s6, s6, 0x40000
	s_addc_u32 s7, s7, 0
	v_add_u32_e32 v32, 0x400, v31
	s_waitcnt vmcnt(30)
	ds_write2_b32 v31, v176, v177 offset1:66
	s_waitcnt vmcnt(28)
	ds_write2_b32 v31, v178, v179 offset0:132 offset1:198
	s_waitcnt vmcnt(26)
	ds_write2_b32 v32, v180, v181 offset0:8 offset1:74
	s_waitcnt vmcnt(24)
	ds_write2_b32 v32, v182, v183 offset0:140 offset1:206
	v_add_u32_e32 v31, 0x840, v31
	v_add_u32_e32 v32, 0x400, v31
	s_waitcnt vmcnt(22)
	ds_write2_b32 v31, v184, v185 offset1:66
	s_waitcnt vmcnt(20)
	ds_write2_b32 v31, v186, v187 offset0:132 offset1:198
	s_waitcnt vmcnt(18)
	ds_write2_b32 v32, v188, v189 offset0:8 offset1:74
	s_waitcnt vmcnt(16)
	ds_write2_b32 v32, v190, v191 offset0:140 offset1:206
	v_add_u32_e32 v31, 0x840, v31
	v_add_u32_e32 v32, 0x400, v31
	s_waitcnt vmcnt(14)
	ds_write2_b32 v31, v192, v193 offset1:66
	s_waitcnt vmcnt(12)
	ds_write2_b32 v31, v194, v195 offset0:132 offset1:198
	s_waitcnt vmcnt(10)
	ds_write2_b32 v32, v196, v197 offset0:8 offset1:74
	s_waitcnt vmcnt(8)
	ds_write2_b32 v32, v198, v199 offset0:140 offset1:206
	v_add_u32_e32 v31, 0x840, v31
	v_add_u32_e32 v32, 0x400, v31
	s_waitcnt vmcnt(6)
	ds_write2_b32 v31, v200, v201 offset1:66
	s_waitcnt vmcnt(4)
	ds_write2_b32 v31, v202, v203 offset0:132 offset1:198
	s_waitcnt vmcnt(2)
	ds_write2_b32 v32, v204, v205 offset0:8 offset1:74
	s_waitcnt vmcnt(0)
	ds_write2_b32 v32, v206, v207 offset0:140 offset1:206
	v_add_u32_e32 v31, 0x840, v31
	s_waitcnt lgkmcnt(0)
	ds_read2_b32 v[8:9], v22 offset0:33 offset1:41
	ds_read2_b32 v[10:11], v22 offset1:8
	ds_read2_b32 v[12:13], v22 offset0:66 offset1:74
	ds_read2_b32 v[14:15], v22 offset0:99 offset1:107
	ds_read2_b32 v[16:17], v22 offset0:132 offset1:140
	ds_read2_b32 v[18:19], v22 offset0:165 offset1:173
	ds_read2_b32 v[32:33], v22 offset0:198 offset1:206
	ds_read2_b32 v[34:35], v22 offset0:231 offset1:239
	s_ashr_i32 s3, s2, 31
	v_lshl_add_u64 v[36:37], s[2:3], 1, v[0:1]
	v_add_u32_e32 v31, s4, v21
	s_waitcnt lgkmcnt(6)
	v_cvt_pk_bf16_f32 v4, v10, v8
	s_waitcnt lgkmcnt(4)
	v_cvt_pk_bf16_f32 v5, v12, v14
	s_waitcnt lgkmcnt(2)
	v_cvt_pk_bf16_f32 v6, v16, v18
	s_waitcnt lgkmcnt(0)
	v_cvt_pk_bf16_f32 v7, v32, v34
	v_mad_i64_i32 v[38:39], s[6:7], v31, s0, v[36:37]
	global_store_dwordx4 v[38:39], v[4:7], off nt
	v_add_u32_e32 v8, 8, v31
	s_nop 0
	v_cvt_pk_bf16_f32 v4, v11, v9
	v_cvt_pk_bf16_f32 v5, v13, v15
	v_cvt_pk_bf16_f32 v6, v17, v19
	v_cvt_pk_bf16_f32 v7, v33, v35
	ds_read2_b32 v[10:11], v22 offset0:49 offset1:57
	ds_read2_b32 v[12:13], v22 offset0:16 offset1:24
	ds_read2_b32 v[14:15], v22 offset0:82 offset1:90
	ds_read2_b32 v[16:17], v22 offset0:115 offset1:123
	ds_read2_b32 v[18:19], v22 offset0:148 offset1:156
	ds_read2_b32 v[32:33], v22 offset0:181 offset1:189
	ds_read2_b32 v[34:35], v22 offset0:214 offset1:222
	ds_read2_b32 v[38:39], v22 offset0:247 offset1:255
	v_mad_i64_i32 v[8:9], s[6:7], v8, s0, v[36:37]
	global_store_dwordx4 v[8:9], v[4:7], off nt
	v_add_u32_e32 v8, 16, v31
	v_mad_i64_i32 v[8:9], s[6:7], v8, s0, v[36:37]
	s_waitcnt lgkmcnt(6)
	v_cvt_pk_bf16_f32 v4, v12, v10
	s_waitcnt lgkmcnt(4)
	v_cvt_pk_bf16_f32 v5, v14, v16
	s_waitcnt lgkmcnt(2)
	v_cvt_pk_bf16_f32 v6, v18, v32
	s_waitcnt lgkmcnt(0)
	v_cvt_pk_bf16_f32 v7, v34, v38
	global_store_dwordx4 v[8:9], v[4:7], off nt
	v_add_u32_e32 v8, 24, v31
	v_mad_i64_i32 v[8:9], s[6:7], v8, s0, v[36:37]
	v_cvt_pk_bf16_f32 v4, v13, v11
	v_cvt_pk_bf16_f32 v5, v15, v17
	v_cvt_pk_bf16_f32 v6, v19, v33
	v_cvt_pk_bf16_f32 v7, v35, v39
	global_store_dwordx4 v[8:9], v[4:7], off nt
	s_waitcnt lgkmcnt(0)
	s_branch .LBB0_1399
